# row phases k=2,k=6: wait for the modulation-vector loads moved after the first trip's row loads (scale/bias ops recomputed per trip)
# baseline (speedup 1.0000x reference)
.LBB0_56:
	s_add_i32 s4, s2, 1
	s_cmp_lt_i32 s4, s6
	s_cselect_b64 s[4:5], -1, 0
	v_cndmask_b32_e64 v64, 0, 1, s[4:5]
	v_mov_b32_e32 v65, s59
	v_add_co_u32_e32 v128, vcc, 0x2000000, v94
	v_lshl_add_u64 v[64:65], v[64:65], 0, s[2:3]
	s_nop 0
	v_addc_co_u32_e32 v129, vcc, 0, v95, vcc
	v_lshl_add_u64 v[64:65], v[64:65], 0, v[72:73]
	global_load_dwordx4 v[100:103], v[128:129], off
	global_load_dwordx4 v[104:107], v[128:129], off offset:1024
	global_load_dwordx4 v[116:119], v[94:95], off
	global_load_dwordx4 v[120:123], v[94:95], off offset:1024
	v_lshlrev_b64 v[64:65], 11, v[64:65]
	v_lshl_add_u64 v[98:99], v[90:91], 0, v[64:65]
	v_lshl_add_u64 v[96:97], v[92:93], 0, v[64:65]
	global_load_dwordx4 v[108:111], v[98:99], off
	global_load_dwordx4 v[124:127], v[98:99], off offset:1024
	global_load_dwordx4 v[68:71], v[96:97], off
	global_load_dwordx4 v[64:67], v[96:97], off offset:1024
	s_waitcnt vmcnt(10)
	v_pk_add_f32 v[78:79], v[218:219], 1.0 op_sel_hi:[1,0]
	v_pk_add_f32 v[74:75], v[222:223], 1.0 op_sel_hi:[1,0]
	v_pk_add_f32 v[76:77], v[220:221], 1.0 op_sel_hi:[1,0]
	v_pk_add_f32 v[80:81], v[216:217], 1.0 op_sel_hi:[1,0]
	v_pk_add_f32 v[88:89], v[224:225], 1.0 op_sel_hi:[1,0]
	v_pk_add_f32 v[82:83], v[230:231], 1.0 op_sel_hi:[1,0]
	v_pk_add_f32 v[84:85], v[228:229], 1.0 op_sel_hi:[1,0]
	v_pk_add_f32 v[86:87], v[226:227], 1.0 op_sel_hi:[1,0]
	s_waitcnt vmcnt(7)
	v_lshlrev_b32_e32 v130, 16, v100
	v_and_b32_e32 v131, 0xffff0000, v100
	v_lshlrev_b32_e32 v150, 16, v101
	v_and_b32_e32 v151, 0xffff0000, v101
	v_lshlrev_b32_e32 v152, 16, v102
	v_and_b32_e32 v153, 0xffff0000, v102
	v_lshlrev_b32_e32 v154, 16, v103
	v_and_b32_e32 v155, 0xffff0000, v103
	s_waitcnt vmcnt(2)
	v_lshlrev_b32_e32 v100, 16, v126
	v_and_b32_e32 v101, 0xffff0000, v126
	v_lshlrev_b32_e32 v102, 16, v127
	v_and_b32_e32 v103, 0xffff0000, v127
	v_and_b32_e32 v127, 0xffff0000, v118
	v_and_b32_e32 v126, 0xffff0000, v116
	v_lshlrev_b32_e32 v156, 16, v104
	v_and_b32_e32 v157, 0xffff0000, v104
	v_lshlrev_b32_e32 v158, 16, v105
	v_and_b32_e32 v159, 0xffff0000, v105
	v_lshlrev_b32_e32 v160, 16, v106
	v_and_b32_e32 v161, 0xffff0000, v106
	v_lshlrev_b32_e32 v162, 16, v107
	v_and_b32_e32 v163, 0xffff0000, v107
	v_lshlrev_b32_e32 v104, 16, v124
	v_and_b32_e32 v105, 0xffff0000, v124
	v_lshlrev_b32_e32 v106, 16, v125
	v_and_b32_e32 v107, 0xffff0000, v125
	v_lshlrev_b32_e32 v125, 16, v118
	v_lshlrev_b32_e32 v124, 16, v116
	v_lshlrev_b32_e32 v164, 16, v117
	v_and_b32_e32 v118, 0xffff0000, v117
	v_pk_mul_f32 v[116:117], v[126:127], v[126:127]
	v_and_b32_e32 v169, 0xffff0000, v120
	v_and_b32_e32 v168, 0xffff0000, v122
	v_lshlrev_b32_e32 v165, 16, v119
	v_pk_fma_f32 v[116:117], v[124:125], v[124:125], v[116:117]
	v_lshlrev_b32_e32 v167, 16, v120
	v_lshlrev_b32_e32 v166, 16, v122
	v_lshlrev_b32_e32 v170, 16, v123
	v_and_b32_e32 v120, 0xffff0000, v123
	v_pk_mul_f32 v[122:123], v[168:169], v[168:169]
	v_and_b32_e32 v119, 0xffff0000, v119
	v_pk_fma_f32 v[116:117], v[164:165], v[164:165], v[116:117]
	v_lshlrev_b32_e32 v171, 16, v121
	v_pk_fma_f32 v[122:123], v[166:167], v[166:167], v[122:123]
	v_pk_fma_f32 v[116:117], v[118:119], v[118:119], v[116:117]
	v_and_b32_e32 v121, 0xffff0000, v121
	v_pk_fma_f32 v[122:123], v[170:171], v[170:171], v[122:123]
	v_add_f32_e32 v116, v116, v117
	v_pk_fma_f32 v[122:123], v[120:121], v[120:121], v[122:123]
	v_mov_b32_e32 v173, v126
	v_add_f32_e32 v116, v116, v123
	v_add_f32_e32 v116, v122, v116
	v_mov_b32_e32 v123, v118
	v_mov_b32_e32 v118, v165
	v_add_f32_dpp v116, v116, v116 quad_perm:[1,0,3,2] row_mask:0xf bank_mask:0xf bound_ctrl:1
	v_mov_b32_e32 v126, v125
	v_mov_b32_e32 v122, v164
	v_add_f32_dpp v116, v116, v116 quad_perm:[2,3,0,1] row_mask:0xf bank_mask:0xf bound_ctrl:1
	v_mov_b32_e32 v172, v124
	v_lshlrev_b32_e32 v114, 16, v109
	v_add_f32_dpp v116, v116, v116 row_half_mirror row_mask:0xf bank_mask:0xf bound_ctrl:1
	v_and_b32_e32 v115, 0xffff0000, v109
	v_lshlrev_b32_e32 v112, 16, v108
	v_add_f32_dpp v116, v116, v116 row_mirror row_mask:0xf bank_mask:0xf bound_ctrl:1
	v_and_b32_e32 v113, 0xffff0000, v108
	v_readlane_b32 s7, v116, 16
	v_readlane_b32 s8, v116, 48
	v_readlane_b32 s4, v116, 0
	v_readlane_b32 s5, v116, 32
	v_mov_b32_e32 v116, s7
	v_mov_b32_e32 v117, s8
	v_pk_add_f32 v[116:117], s[4:5], v[116:117]
	v_lshlrev_b32_e32 v108, 16, v110
	v_add_f32_e32 v116, v116, v117
	v_fmamk_f32 v116, v116, 0x3a800000, v137
	v_cmp_gt_f32_e32 vcc, s94, v116
	v_mul_f32_e32 v117, 0x4b800000, v116
	v_and_b32_e32 v109, 0xffff0000, v110
	v_cndmask_b32_e32 v116, v116, v117, vcc
	v_rsq_f32_e32 v116, v116
	v_lshlrev_b32_e32 v110, 16, v111
	v_and_b32_e32 v111, 0xffff0000, v111
	s_add_u32 s2, s2, 2
	v_mul_f32_e32 v117, 0x45800000, v116
	v_cndmask_b32_e32 v116, v116, v117, vcc
	v_pk_mul_f32 v[118:119], v[116:117], v[118:119] op_sel_hi:[0,1]
	v_pk_mul_f32 v[118:119], v[10:11], v[118:119]
	v_pk_mul_f32 v[124:125], v[116:117], v[126:127] op_sel_hi:[0,1]
	v_pk_fma_f32 v[126:127], v[2:3], v[118:119], v[154:155]
	v_mov_b32_e32 v118, v171
	v_mov_b32_e32 v119, v121
	v_pk_mul_f32 v[122:123], v[116:117], v[122:123] op_sel_hi:[0,1]
	v_pk_mul_f32 v[118:119], v[116:117], v[118:119] op_sel_hi:[0,1]
	v_pk_mul_f32 v[122:123], v[14:15], v[122:123]
	v_pk_mul_f32 v[124:125], v[8:9], v[124:125]
	v_pk_mul_f32 v[118:119], v[30:31], v[118:119]
	v_mov_b32_e32 v171, v120
	v_pk_fma_f32 v[122:123], v[6:7], v[122:123], v[150:151]
	v_pk_fma_f32 v[124:125], v[0:1], v[124:125], v[152:153]
	v_mov_b32_e32 v150, v167
	v_mov_b32_e32 v151, v169
	v_pk_fma_f32 v[152:153], v[22:23], v[118:119], v[158:159]
	v_pk_mul_f32 v[118:119], v[116:117], v[170:171] op_sel_hi:[0,1]
	v_mov_b32_e32 v167, v168
	v_pk_mul_f32 v[172:173], v[116:117], v[172:173] op_sel_hi:[0,1]
	v_pk_mul_f32 v[150:151], v[116:117], v[150:151] op_sel_hi:[0,1]
	v_pk_mul_f32 v[116:117], v[116:117], v[166:167] op_sel_hi:[0,1]
	v_pk_mul_f32 v[118:119], v[26:27], v[118:119]
	v_pk_mul_f32 v[172:173], v[12:13], v[172:173]
	v_pk_mul_f32 v[116:117], v[24:25], v[116:117]
	v_pk_fma_f32 v[120:121], v[18:19], v[118:119], v[162:163]
	v_cvt_pk_bf16_f32 v118, v124, v125
	v_cvt_pk_bf16_f32 v119, v126, v127
	v_pk_fma_f32 v[130:131], v[4:5], v[172:173], v[130:131]
	v_pk_mul_f32 v[150:151], v[28:29], v[150:151]
	v_pk_fma_f32 v[154:155], v[16:17], v[116:117], v[160:161]
	v_cvt_pk_bf16_f32 v116, v130, v131
	v_cvt_pk_bf16_f32 v117, v122, v123
	global_store_dwordx4 v[128:129], v[116:119], off
	v_pk_fma_f32 v[150:151], v[20:21], v[150:151], v[156:157]
	s_addc_u32 s3, s3, 0
	v_cvt_pk_bf16_f32 v118, v154, v155
	v_cvt_pk_bf16_f32 v119, v120, v121
	v_cvt_pk_bf16_f32 v116, v150, v151
	v_cvt_pk_bf16_f32 v117, v152, v153
	global_store_dwordx4 v[128:129], v[116:119], off offset:1024
	v_mov_b32_e32 v128, v155
	v_mov_b32_e32 v129, v151
	v_mov_b32_e32 v118, v131
	v_mov_b32_e32 v119, v125
	v_mov_b32_e32 v116, v130
	v_mov_b32_e32 v117, v124
	v_pk_mul_f32 v[118:119], v[118:119], v[118:119]
	v_pk_mul_f32 v[128:129], v[128:129], v[128:129]
	v_pk_fma_f32 v[116:117], v[116:117], v[116:117], v[118:119]
	v_mov_b32_e32 v118, v122
	v_mov_b32_e32 v119, v126
	v_pk_fma_f32 v[116:117], v[118:119], v[118:119], v[116:117]
	v_mov_b32_e32 v118, v123
	v_mov_b32_e32 v119, v127
	v_pk_fma_f32 v[116:117], v[118:119], v[118:119], v[116:117]
	v_mov_b32_e32 v118, v154
	v_mov_b32_e32 v119, v150
	v_pk_fma_f32 v[118:119], v[118:119], v[118:119], v[128:129]
	v_mov_b32_e32 v128, v120
	v_mov_b32_e32 v129, v152
	v_pk_fma_f32 v[118:119], v[128:129], v[128:129], v[118:119]
	v_mov_b32_e32 v128, v121
	v_mov_b32_e32 v129, v153
	v_pk_fma_f32 v[118:119], v[128:129], v[128:129], v[118:119]
	v_add_f32_e32 v116, v116, v117
	v_add_f32_e32 v116, v119, v116
	v_add_f32_e32 v116, v118, v116
	s_cmp_ge_i32 s2, s6
	s_nop 0
	v_add_f32_dpp v116, v116, v116 quad_perm:[1,0,3,2] row_mask:0xf bank_mask:0xf bound_ctrl:1
	s_nop 1
	v_add_f32_dpp v116, v116, v116 quad_perm:[2,3,0,1] row_mask:0xf bank_mask:0xf bound_ctrl:1
	s_nop 1
	v_add_f32_dpp v116, v116, v116 row_half_mirror row_mask:0xf bank_mask:0xf bound_ctrl:1
	s_nop 1
	v_add_f32_dpp v116, v116, v116 row_mirror row_mask:0xf bank_mask:0xf bound_ctrl:1
	s_nop 0
	v_readlane_b32 s7, v116, 16
	v_readlane_b32 s8, v116, 48
	v_readlane_b32 s4, v116, 0
	v_readlane_b32 s5, v116, 32
	v_mov_b32_e32 v116, s7
	v_mov_b32_e32 v117, s8
	v_pk_add_f32 v[116:117], s[4:5], v[116:117]
	s_nop 0
	v_add_f32_e32 v116, v116, v117
	v_fmamk_f32 v116, v116, 0x3a800000, v137
	v_cmp_gt_f32_e32 vcc, s94, v116
	v_mul_f32_e32 v117, 0x4b800000, v116
	s_nop 0
	v_cndmask_b32_e32 v116, v116, v117, vcc
	v_rsq_f32_e32 v116, v116
	s_nop 0
	v_mul_f32_e32 v117, 0x45800000, v116
	v_cndmask_b32_e32 v116, v116, v117, vcc
	v_pk_mul_f32 v[118:119], v[122:123], v[116:117] op_sel_hi:[1,0]
	v_pk_mul_f32 v[122:123], v[130:131], v[116:117] op_sel_hi:[1,0]
	v_pk_mul_f32 v[118:119], v[46:47], v[118:119]
	v_pk_mul_f32 v[126:127], v[126:127], v[116:117] op_sel_hi:[1,0]
	v_pk_mul_f32 v[124:125], v[124:125], v[116:117] op_sel_hi:[1,0]
	v_pk_mul_f32 v[128:129], v[152:153], v[116:117] op_sel_hi:[1,0]
	v_pk_mul_f32 v[130:131], v[150:151], v[116:117] op_sel_hi:[1,0]
	v_pk_mul_f32 v[120:121], v[120:121], v[116:117] op_sel_hi:[1,0]
	v_pk_mul_f32 v[116:117], v[154:155], v[116:117] op_sel_hi:[1,0]
	v_pk_fma_f32 v[118:119], v[74:75], v[118:119], v[38:39]
	v_pk_mul_f32 v[124:125], v[40:41], v[124:125]
	v_pk_mul_f32 v[126:127], v[42:43], v[126:127]
	v_pk_mul_f32 v[116:117], v[56:57], v[116:117]
	v_pk_mul_f32 v[122:123], v[44:45], v[122:123]
	v_pk_fma_f32 v[126:127], v[78:79], v[126:127], v[34:35]
	v_pk_fma_f32 v[124:125], v[80:81], v[124:125], v[32:33]
	v_pk_mul_f32 v[120:121], v[58:59], v[120:121]
	v_pk_fma_f32 v[150:151], v[88:89], v[116:117], v[48:49]
	v_cvt_pk_bf16_f32 v117, v118, v119
	v_cvt_pk_bf16_f32 v118, v124, v125
	v_cvt_pk_bf16_f32 v119, v126, v127
	v_pk_fma_f32 v[122:123], v[76:77], v[122:123], v[36:37]
	v_pk_mul_f32 v[130:131], v[60:61], v[130:131]
	v_pk_mul_f32 v[128:129], v[62:63], v[128:129]
	v_pk_fma_f32 v[120:121], v[86:87], v[120:121], v[50:51]
	v_cvt_pk_bf16_f32 v116, v122, v123
	global_store_dwordx4 v[94:95], v[116:119], off
	v_pk_fma_f32 v[128:129], v[82:83], v[128:129], v[54:55]
	v_pk_fma_f32 v[130:131], v[84:85], v[130:131], v[52:53]
	v_cvt_pk_bf16_f32 v118, v150, v151
	v_cvt_pk_bf16_f32 v119, v120, v121
	v_cvt_pk_bf16_f32 v117, v128, v129
	s_waitcnt vmcnt(4)
	v_lshlrev_b32_e32 v120, 16, v69
	v_cvt_pk_bf16_f32 v116, v130, v131
	global_store_dwordx4 v[94:95], v[116:119], off offset:1024
	s_waitcnt vmcnt(4)
	v_and_b32_e32 v125, 0xffff0000, v64
	v_and_b32_e32 v124, 0xffff0000, v66
	v_and_b32_e32 v119, 0xffff0000, v70
	v_and_b32_e32 v118, 0xffff0000, v68
	v_lshlrev_b32_e32 v117, 16, v70
	v_lshlrev_b32_e32 v116, 16, v68
	v_and_b32_e32 v70, 0xffff0000, v69
	v_pk_mul_f32 v[68:69], v[118:119], v[118:119]
	v_lshlrev_b32_e32 v121, 16, v71
	v_pk_fma_f32 v[68:69], v[116:117], v[116:117], v[68:69]
	v_lshlrev_b32_e32 v123, 16, v64
	v_lshlrev_b32_e32 v122, 16, v66
	v_lshlrev_b32_e32 v126, 16, v67
	v_and_b32_e32 v64, 0xffff0000, v67
	v_pk_mul_f32 v[66:67], v[124:125], v[124:125]
	v_and_b32_e32 v71, 0xffff0000, v71
	v_pk_fma_f32 v[68:69], v[120:121], v[120:121], v[68:69]
	v_lshlrev_b32_e32 v127, 16, v65
	v_pk_fma_f32 v[66:67], v[122:123], v[122:123], v[66:67]
	v_pk_fma_f32 v[68:69], v[70:71], v[70:71], v[68:69]
	v_and_b32_e32 v65, 0xffff0000, v65
	v_pk_fma_f32 v[66:67], v[126:127], v[126:127], v[66:67]
	v_add_f32_e32 v68, v68, v69
	v_pk_fma_f32 v[66:67], v[64:65], v[64:65], v[66:67]
	v_mov_b32_e32 v69, v70
	v_add_f32_e32 v67, v68, v67
	v_add_f32_e32 v66, v66, v67
	v_mov_b32_e32 v68, v120
	v_mov_b32_e32 v129, v118
	v_add_f32_dpp v66, v66, v66 quad_perm:[1,0,3,2] row_mask:0xf bank_mask:0xf bound_ctrl:1
	v_mov_b32_e32 v70, v121
	v_mov_b32_e32 v118, v117
	v_add_f32_dpp v66, v66, v66 quad_perm:[2,3,0,1] row_mask:0xf bank_mask:0xf bound_ctrl:1
	v_mov_b32_e32 v128, v116
	v_lshl_add_u64 v[94:95], v[94:95], 0, s[30:31]
	v_add_f32_dpp v66, v66, v66 row_half_mirror row_mask:0xf bank_mask:0xf bound_ctrl:1
	s_nop 1
	v_add_f32_dpp v66, v66, v66 row_mirror row_mask:0xf bank_mask:0xf bound_ctrl:1
	s_nop 0
	v_readlane_b32 s7, v66, 16
	v_readlane_b32 s8, v66, 48
	v_readlane_b32 s4, v66, 0
	v_readlane_b32 s5, v66, 32
	v_mov_b32_e32 v66, s7
	v_mov_b32_e32 v67, s8
	v_pk_add_f32 v[66:67], s[4:5], v[66:67]
	s_nop 0
	v_add_f32_e32 v66, v66, v67
	v_fmamk_f32 v66, v66, 0x3a800000, v137
	v_cmp_gt_f32_e32 vcc, s94, v66
	v_mul_f32_e32 v67, 0x4b800000, v66
	s_nop 0
	v_cndmask_b32_e32 v66, v66, v67, vcc
	v_rsq_f32_e32 v66, v66
	s_nop 0
	v_mul_f32_e32 v67, 0x45800000, v66
	v_cndmask_b32_e32 v66, v66, v67, vcc
	v_pk_mul_f32 v[68:69], v[66:67], v[68:69] op_sel_hi:[0,1]
	v_pk_mul_f32 v[68:69], v[14:15], v[68:69]
	v_pk_mul_f32 v[70:71], v[66:67], v[70:71] op_sel_hi:[0,1]
	v_pk_fma_f32 v[68:69], v[6:7], v[68:69], v[114:115]
	v_pk_mul_f32 v[114:115], v[66:67], v[118:119] op_sel_hi:[0,1]
	v_pk_mul_f32 v[114:115], v[8:9], v[114:115]
	v_pk_mul_f32 v[70:71], v[10:11], v[70:71]
	v_pk_fma_f32 v[108:109], v[0:1], v[114:115], v[108:109]
	v_pk_fma_f32 v[70:71], v[2:3], v[70:71], v[110:111]
	v_mov_b32_e32 v110, v127
	v_mov_b32_e32 v111, v65
	v_mov_b32_e32 v114, v123
	v_mov_b32_e32 v115, v125
	v_mov_b32_e32 v127, v64
	v_mov_b32_e32 v123, v124
	v_pk_mul_f32 v[128:129], v[66:67], v[128:129] op_sel_hi:[0,1]
	v_pk_mul_f32 v[110:111], v[66:67], v[110:111] op_sel_hi:[0,1]
	v_pk_mul_f32 v[114:115], v[66:67], v[114:115] op_sel_hi:[0,1]
	v_pk_mul_f32 v[64:65], v[66:67], v[126:127] op_sel_hi:[0,1]
	v_pk_mul_f32 v[66:67], v[66:67], v[122:123] op_sel_hi:[0,1]
	v_pk_mul_f32 v[66:67], v[24:25], v[66:67]
	v_pk_mul_f32 v[128:129], v[12:13], v[128:129]
	v_pk_mul_f32 v[64:65], v[26:27], v[64:65]
	v_pk_fma_f32 v[100:101], v[16:17], v[66:67], v[100:101]
	v_cvt_pk_bf16_f32 v66, v108, v109
	v_cvt_pk_bf16_f32 v67, v70, v71
	v_pk_fma_f32 v[112:113], v[4:5], v[128:129], v[112:113]
	v_pk_mul_f32 v[114:115], v[28:29], v[114:115]
	v_pk_mul_f32 v[110:111], v[30:31], v[110:111]
	v_pk_fma_f32 v[102:103], v[18:19], v[64:65], v[102:103]
	v_cvt_pk_bf16_f32 v64, v112, v113
	v_cvt_pk_bf16_f32 v65, v68, v69
	global_store_dwordx4 v[98:99], v[64:67], off
	v_pk_fma_f32 v[106:107], v[22:23], v[110:111], v[106:107]
	v_pk_fma_f32 v[104:105], v[20:21], v[114:115], v[104:105]
	v_cvt_pk_bf16_f32 v66, v100, v101
	v_cvt_pk_bf16_f32 v67, v102, v103
	v_cvt_pk_bf16_f32 v65, v106, v107
	s_nop 0
	v_cvt_pk_bf16_f32 v64, v104, v105
	global_store_dwordx4 v[98:99], v[64:67], off offset:1024
	v_mov_b32_e32 v98, v101
	v_mov_b32_e32 v99, v105
	v_mov_b32_e32 v66, v113
	v_mov_b32_e32 v67, v109
	v_mov_b32_e32 v64, v112
	v_mov_b32_e32 v65, v108
	v_pk_mul_f32 v[66:67], v[66:67], v[66:67]
	v_pk_mul_f32 v[98:99], v[98:99], v[98:99]
	v_pk_fma_f32 v[64:65], v[64:65], v[64:65], v[66:67]
	v_mov_b32_e32 v66, v68
	v_mov_b32_e32 v67, v70
	v_pk_fma_f32 v[64:65], v[66:67], v[66:67], v[64:65]
	v_mov_b32_e32 v66, v69
	v_mov_b32_e32 v67, v71
	v_pk_fma_f32 v[64:65], v[66:67], v[66:67], v[64:65]
	v_mov_b32_e32 v66, v100
	v_mov_b32_e32 v67, v104
	v_pk_fma_f32 v[66:67], v[66:67], v[66:67], v[98:99]
	v_mov_b32_e32 v98, v102
	v_mov_b32_e32 v99, v106
	v_pk_fma_f32 v[66:67], v[98:99], v[98:99], v[66:67]
	v_mov_b32_e32 v98, v103
	v_mov_b32_e32 v99, v107
	v_pk_fma_f32 v[66:67], v[98:99], v[98:99], v[66:67]
	v_add_f32_e32 v64, v64, v65
	v_add_f32_e32 v64, v67, v64
	v_add_f32_e32 v64, v66, v64
	s_nop 1
	v_add_f32_dpp v64, v64, v64 quad_perm:[1,0,3,2] row_mask:0xf bank_mask:0xf bound_ctrl:1
	s_nop 1
	v_add_f32_dpp v64, v64, v64 quad_perm:[2,3,0,1] row_mask:0xf bank_mask:0xf bound_ctrl:1
	s_nop 1
	v_add_f32_dpp v64, v64, v64 row_half_mirror row_mask:0xf bank_mask:0xf bound_ctrl:1
	s_nop 1
	v_add_f32_dpp v64, v64, v64 row_mirror row_mask:0xf bank_mask:0xf bound_ctrl:1
	s_nop 0
	v_readlane_b32 s7, v64, 16
	v_readlane_b32 s8, v64, 48
	v_readlane_b32 s4, v64, 0
	v_readlane_b32 s5, v64, 32
	v_mov_b32_e32 v64, s7
	v_mov_b32_e32 v65, s8
	v_pk_add_f32 v[64:65], s[4:5], v[64:65]
	s_nop 0
	v_add_f32_e32 v64, v64, v65
	v_fmamk_f32 v64, v64, 0x3a800000, v137
	v_cmp_gt_f32_e32 vcc, s94, v64
	v_mul_f32_e32 v65, 0x4b800000, v64
	s_nop 0
	v_cndmask_b32_e32 v64, v64, v65, vcc
	v_rsq_f32_e32 v64, v64
	s_nop 0
	v_mul_f32_e32 v65, 0x45800000, v64
	v_cndmask_b32_e32 v64, v64, v65, vcc
	v_pk_mul_f32 v[66:67], v[68:69], v[64:65] op_sel_hi:[1,0]
	v_pk_mul_f32 v[68:69], v[112:113], v[64:65] op_sel_hi:[1,0]
	v_pk_mul_f32 v[66:67], v[46:47], v[66:67]
	v_pk_mul_f32 v[70:71], v[70:71], v[64:65] op_sel_hi:[1,0]
	v_pk_mul_f32 v[98:99], v[108:109], v[64:65] op_sel_hi:[1,0]
	v_pk_mul_f32 v[106:107], v[106:107], v[64:65] op_sel_hi:[1,0]
	v_pk_mul_f32 v[104:105], v[104:105], v[64:65] op_sel_hi:[1,0]
	v_pk_mul_f32 v[102:103], v[102:103], v[64:65] op_sel_hi:[1,0]
	v_pk_mul_f32 v[64:65], v[100:101], v[64:65] op_sel_hi:[1,0]
	v_pk_mul_f32 v[68:69], v[44:45], v[68:69]
	v_pk_fma_f32 v[66:67], v[74:75], v[66:67], v[38:39]
	v_pk_mul_f32 v[98:99], v[40:41], v[98:99]
	v_pk_mul_f32 v[70:71], v[42:43], v[70:71]
	v_pk_mul_f32 v[64:65], v[56:57], v[64:65]
	v_pk_fma_f32 v[68:69], v[76:77], v[68:69], v[36:37]
	v_pk_fma_f32 v[70:71], v[78:79], v[70:71], v[34:35]
	v_pk_fma_f32 v[98:99], v[80:81], v[98:99], v[32:33]
	v_pk_mul_f32 v[104:105], v[60:61], v[104:105]
	v_pk_mul_f32 v[106:107], v[62:63], v[106:107]
	v_pk_mul_f32 v[100:101], v[58:59], v[102:103]
	v_pk_fma_f32 v[102:103], v[88:89], v[64:65], v[48:49]
	v_cvt_pk_bf16_f32 v64, v68, v69
	v_cvt_pk_bf16_f32 v65, v66, v67
	v_cvt_pk_bf16_f32 v66, v98, v99
	v_cvt_pk_bf16_f32 v67, v70, v71
	v_pk_fma_f32 v[106:107], v[82:83], v[106:107], v[54:55]
	v_pk_fma_f32 v[104:105], v[84:85], v[104:105], v[52:53]
	v_pk_fma_f32 v[100:101], v[86:87], v[100:101], v[50:51]
	global_store_dwordx4 v[96:97], v[64:67], off
	s_nop 1
	v_cvt_pk_bf16_f32 v64, v104, v105
	v_cvt_pk_bf16_f32 v65, v106, v107
	v_cvt_pk_bf16_f32 v66, v102, v103
	v_cvt_pk_bf16_f32 v67, v100, v101
	global_store_dwordx4 v[96:97], v[64:67], off offset:1024
	s_cbranch_scc0 .LBB0_56

.LBB0_1086:
	s_add_i32 s4, s2, 1
	s_cmp_lt_i32 s4, s8
	s_cselect_b64 s[4:5], -1, 0
	v_cndmask_b32_e64 v48, 0, 1, s[4:5]
	v_mov_b32_e32 v49, s59
	v_add_co_u32_e32 v128, vcc, 0x2000000, v94
	v_lshl_add_u64 v[48:49], v[48:49], 0, s[2:3]
	s_nop 0
	v_addc_co_u32_e32 v129, vcc, 0, v95, vcc
	v_lshl_add_u64 v[48:49], v[48:49], 0, v[56:57]
	global_load_dwordx4 v[100:103], v[128:129], off
	global_load_dwordx4 v[104:107], v[128:129], off offset:1024
	global_load_dwordx4 v[116:119], v[94:95], off
	global_load_dwordx4 v[120:123], v[94:95], off offset:1024
	v_lshlrev_b64 v[48:49], 11, v[48:49]
	v_lshl_add_u64 v[98:99], v[90:91], 0, v[48:49]
	v_lshl_add_u64 v[96:97], v[92:93], 0, v[48:49]
	global_load_dwordx4 v[108:111], v[98:99], off
	global_load_dwordx4 v[124:127], v[98:99], off offset:1024
	global_load_dwordx4 v[52:55], v[96:97], off
	global_load_dwordx4 v[48:51], v[96:97], off offset:1024
	s_waitcnt vmcnt(10)
	v_pk_mul_f32 v[64:65], v[216:217], 0.5 op_sel_hi:[1,0]
	v_pk_mul_f32 v[58:59], v[222:223], 0.5 op_sel_hi:[1,0]
	v_pk_mul_f32 v[60:61], v[220:221], 0.5 op_sel_hi:[1,0]
	v_pk_mul_f32 v[62:63], v[218:219], 0.5 op_sel_hi:[1,0]
	v_pk_mul_f32 v[70:71], v[226:227], 0.5 op_sel_hi:[1,0]
	v_pk_mul_f32 v[66:67], v[230:231], 0.5 op_sel_hi:[1,0]
	v_pk_mul_f32 v[68:69], v[228:229], 0.5 op_sel_hi:[1,0]
	v_pk_mul_f32 v[72:73], v[224:225], 0.5 op_sel_hi:[1,0]
	v_pk_add_f32 v[78:79], v[234:235], 1.0 op_sel_hi:[1,0]
	v_pk_add_f32 v[74:75], v[238:239], 1.0 op_sel_hi:[1,0]
	v_pk_add_f32 v[76:77], v[236:237], 1.0 op_sel_hi:[1,0]
	v_pk_add_f32 v[80:81], v[232:233], 1.0 op_sel_hi:[1,0]
	v_pk_add_f32 v[88:89], v[240:241], 1.0 op_sel_hi:[1,0]
	v_pk_add_f32 v[82:83], v[246:247], 1.0 op_sel_hi:[1,0]
	v_pk_add_f32 v[84:85], v[244:245], 1.0 op_sel_hi:[1,0]
	v_pk_add_f32 v[86:87], v[242:243], 1.0 op_sel_hi:[1,0]
	s_waitcnt vmcnt(7)
	v_lshlrev_b32_e32 v130, 16, v100
	v_and_b32_e32 v131, 0xffff0000, v100
	v_lshlrev_b32_e32 v150, 16, v101
	v_and_b32_e32 v151, 0xffff0000, v101
	v_lshlrev_b32_e32 v152, 16, v102
	v_and_b32_e32 v153, 0xffff0000, v102
	v_lshlrev_b32_e32 v154, 16, v103
	v_and_b32_e32 v155, 0xffff0000, v103
	s_waitcnt vmcnt(2)
	v_lshlrev_b32_e32 v100, 16, v126
	v_and_b32_e32 v101, 0xffff0000, v126
	v_lshlrev_b32_e32 v102, 16, v127
	v_and_b32_e32 v103, 0xffff0000, v127
	v_and_b32_e32 v127, 0xffff0000, v118
	v_and_b32_e32 v126, 0xffff0000, v116
	v_lshlrev_b32_e32 v156, 16, v104
	v_and_b32_e32 v157, 0xffff0000, v104
	v_lshlrev_b32_e32 v158, 16, v105
	v_and_b32_e32 v159, 0xffff0000, v105
	v_lshlrev_b32_e32 v160, 16, v106
	v_and_b32_e32 v161, 0xffff0000, v106
	v_lshlrev_b32_e32 v162, 16, v107
	v_and_b32_e32 v163, 0xffff0000, v107
	v_lshlrev_b32_e32 v104, 16, v124
	v_and_b32_e32 v105, 0xffff0000, v124
	v_lshlrev_b32_e32 v106, 16, v125
	v_and_b32_e32 v107, 0xffff0000, v125
	v_lshlrev_b32_e32 v125, 16, v118
	v_lshlrev_b32_e32 v124, 16, v116
	v_lshlrev_b32_e32 v164, 16, v117
	v_and_b32_e32 v118, 0xffff0000, v117
	v_pk_mul_f32 v[116:117], v[126:127], v[126:127]
	v_and_b32_e32 v169, 0xffff0000, v120
	v_and_b32_e32 v168, 0xffff0000, v122
	v_lshlrev_b32_e32 v165, 16, v119
	v_pk_fma_f32 v[116:117], v[124:125], v[124:125], v[116:117]
	v_lshlrev_b32_e32 v167, 16, v120
	v_lshlrev_b32_e32 v166, 16, v122
	v_lshlrev_b32_e32 v170, 16, v123
	v_and_b32_e32 v120, 0xffff0000, v123
	v_pk_mul_f32 v[122:123], v[168:169], v[168:169]
	v_and_b32_e32 v119, 0xffff0000, v119
	v_pk_fma_f32 v[116:117], v[164:165], v[164:165], v[116:117]
	v_lshlrev_b32_e32 v171, 16, v121
	v_pk_fma_f32 v[122:123], v[166:167], v[166:167], v[122:123]
	v_pk_fma_f32 v[116:117], v[118:119], v[118:119], v[116:117]
	v_and_b32_e32 v121, 0xffff0000, v121
	v_pk_fma_f32 v[122:123], v[170:171], v[170:171], v[122:123]
	v_add_f32_e32 v116, v116, v117
	v_pk_fma_f32 v[122:123], v[120:121], v[120:121], v[122:123]
	v_mov_b32_e32 v173, v126
	v_add_f32_e32 v116, v116, v123
	v_add_f32_e32 v116, v122, v116
	v_mov_b32_e32 v123, v118
	v_mov_b32_e32 v118, v165
	v_add_f32_dpp v116, v116, v116 quad_perm:[1,0,3,2] row_mask:0xf bank_mask:0xf bound_ctrl:1
	v_mov_b32_e32 v126, v125
	v_mov_b32_e32 v122, v164
	v_add_f32_dpp v116, v116, v116 quad_perm:[2,3,0,1] row_mask:0xf bank_mask:0xf bound_ctrl:1
	v_mov_b32_e32 v172, v124
	v_lshlrev_b32_e32 v114, 16, v109
	v_add_f32_dpp v116, v116, v116 row_half_mirror row_mask:0xf bank_mask:0xf bound_ctrl:1
	v_and_b32_e32 v115, 0xffff0000, v109
	v_lshlrev_b32_e32 v112, 16, v108
	v_add_f32_dpp v116, v116, v116 row_mirror row_mask:0xf bank_mask:0xf bound_ctrl:1
	v_and_b32_e32 v113, 0xffff0000, v108
	v_readlane_b32 s6, v116, 16
	v_readlane_b32 s7, v116, 48
	v_readlane_b32 s4, v116, 0
	v_readlane_b32 s5, v116, 32
	v_mov_b32_e32 v116, s6
	v_mov_b32_e32 v117, s7
	v_pk_add_f32 v[116:117], s[4:5], v[116:117]
	v_lshlrev_b32_e32 v108, 16, v110
	v_add_f32_e32 v116, v116, v117
	v_fmamk_f32 v116, v116, 0x3a800000, v137
	v_cmp_gt_f32_e32 vcc, s94, v116
	v_mul_f32_e32 v117, 0x4b800000, v116
	v_and_b32_e32 v109, 0xffff0000, v110
	v_cndmask_b32_e32 v116, v116, v117, vcc
	v_rsq_f32_e32 v116, v116
	v_lshlrev_b32_e32 v110, 16, v111
	v_and_b32_e32 v111, 0xffff0000, v111
	s_add_u32 s2, s2, 2
	v_mul_f32_e32 v117, 0x45800000, v116
	v_cndmask_b32_e32 v116, v116, v117, vcc
	v_pk_mul_f32 v[118:119], v[116:117], v[118:119] op_sel_hi:[0,1]
	v_pk_mul_f32 v[118:119], v[2:3], v[118:119]
	v_pk_mul_f32 v[124:125], v[116:117], v[126:127] op_sel_hi:[0,1]
	v_pk_fma_f32 v[126:127], v[62:63], v[118:119], v[154:155]
	v_mov_b32_e32 v118, v171
	v_mov_b32_e32 v119, v121
	v_pk_mul_f32 v[122:123], v[116:117], v[122:123] op_sel_hi:[0,1]
	v_pk_mul_f32 v[118:119], v[116:117], v[118:119] op_sel_hi:[0,1]
	v_pk_mul_f32 v[122:123], v[6:7], v[122:123]
	v_pk_mul_f32 v[124:125], v[0:1], v[124:125]
	v_pk_mul_f32 v[118:119], v[14:15], v[118:119]
	v_mov_b32_e32 v171, v120
	v_pk_fma_f32 v[122:123], v[58:59], v[122:123], v[150:151]
	v_pk_fma_f32 v[124:125], v[64:65], v[124:125], v[152:153]
	v_mov_b32_e32 v150, v167
	v_mov_b32_e32 v151, v169
	v_pk_fma_f32 v[152:153], v[66:67], v[118:119], v[158:159]
	v_pk_mul_f32 v[118:119], v[116:117], v[170:171] op_sel_hi:[0,1]
	v_mov_b32_e32 v167, v168
	v_pk_mul_f32 v[172:173], v[116:117], v[172:173] op_sel_hi:[0,1]
	v_pk_mul_f32 v[150:151], v[116:117], v[150:151] op_sel_hi:[0,1]
	v_pk_mul_f32 v[116:117], v[116:117], v[166:167] op_sel_hi:[0,1]
	v_pk_mul_f32 v[118:119], v[10:11], v[118:119]
	v_pk_mul_f32 v[172:173], v[4:5], v[172:173]
	v_pk_mul_f32 v[116:117], v[8:9], v[116:117]
	v_pk_fma_f32 v[120:121], v[70:71], v[118:119], v[162:163]
	v_cvt_pk_bf16_f32 v118, v124, v125
	v_cvt_pk_bf16_f32 v119, v126, v127
	v_pk_fma_f32 v[130:131], v[60:61], v[172:173], v[130:131]
	v_pk_mul_f32 v[150:151], v[12:13], v[150:151]
	v_pk_fma_f32 v[154:155], v[72:73], v[116:117], v[160:161]
	v_cvt_pk_bf16_f32 v116, v130, v131
	v_cvt_pk_bf16_f32 v117, v122, v123
	global_store_dwordx4 v[128:129], v[116:119], off
	v_pk_fma_f32 v[150:151], v[68:69], v[150:151], v[156:157]
	s_addc_u32 s3, s3, 0
	v_cvt_pk_bf16_f32 v118, v154, v155
	v_cvt_pk_bf16_f32 v119, v120, v121
	v_cvt_pk_bf16_f32 v116, v150, v151
	v_cvt_pk_bf16_f32 v117, v152, v153
	global_store_dwordx4 v[128:129], v[116:119], off offset:1024
	v_mov_b32_e32 v128, v155
	v_mov_b32_e32 v129, v151
	v_mov_b32_e32 v118, v131
	v_mov_b32_e32 v119, v125
	v_mov_b32_e32 v116, v130
	v_mov_b32_e32 v117, v124
	v_pk_mul_f32 v[118:119], v[118:119], v[118:119]
	v_pk_mul_f32 v[128:129], v[128:129], v[128:129]
	v_pk_fma_f32 v[116:117], v[116:117], v[116:117], v[118:119]
	v_mov_b32_e32 v118, v122
	v_mov_b32_e32 v119, v126
	v_pk_fma_f32 v[116:117], v[118:119], v[118:119], v[116:117]
	v_mov_b32_e32 v118, v123
	v_mov_b32_e32 v119, v127
	v_pk_fma_f32 v[116:117], v[118:119], v[118:119], v[116:117]
	v_mov_b32_e32 v118, v154
	v_mov_b32_e32 v119, v150
	v_pk_fma_f32 v[118:119], v[118:119], v[118:119], v[128:129]
	v_mov_b32_e32 v128, v120
	v_mov_b32_e32 v129, v152
	v_pk_fma_f32 v[118:119], v[128:129], v[128:129], v[118:119]
	v_mov_b32_e32 v128, v121
	v_mov_b32_e32 v129, v153
	v_pk_fma_f32 v[118:119], v[128:129], v[128:129], v[118:119]
	v_add_f32_e32 v116, v116, v117
	v_add_f32_e32 v116, v119, v116
	v_add_f32_e32 v116, v118, v116
	s_cmp_lt_i32 s2, s8
	s_nop 0
	v_add_f32_dpp v116, v116, v116 quad_perm:[1,0,3,2] row_mask:0xf bank_mask:0xf bound_ctrl:1
	s_nop 1
	v_add_f32_dpp v116, v116, v116 quad_perm:[2,3,0,1] row_mask:0xf bank_mask:0xf bound_ctrl:1
	s_nop 1
	v_add_f32_dpp v116, v116, v116 row_half_mirror row_mask:0xf bank_mask:0xf bound_ctrl:1
	s_nop 1
	v_add_f32_dpp v116, v116, v116 row_mirror row_mask:0xf bank_mask:0xf bound_ctrl:1
	s_nop 0
	v_readlane_b32 s6, v116, 16
	v_readlane_b32 s7, v116, 48
	v_readlane_b32 s4, v116, 0
	v_readlane_b32 s5, v116, 32
	v_mov_b32_e32 v116, s6
	v_mov_b32_e32 v117, s7
	v_pk_add_f32 v[116:117], s[4:5], v[116:117]
	s_nop 0
	v_add_f32_e32 v116, v116, v117
	v_fmamk_f32 v116, v116, 0x3a800000, v137
	v_cmp_gt_f32_e32 vcc, s94, v116
	v_mul_f32_e32 v117, 0x4b800000, v116
	s_nop 0
	v_cndmask_b32_e32 v116, v116, v117, vcc
	v_rsq_f32_e32 v116, v116
	s_nop 0
	v_mul_f32_e32 v117, 0x45800000, v116
	v_cndmask_b32_e32 v116, v116, v117, vcc
	v_pk_mul_f32 v[118:119], v[122:123], v[116:117] op_sel_hi:[1,0]
	v_pk_mul_f32 v[122:123], v[130:131], v[116:117] op_sel_hi:[1,0]
	v_pk_mul_f32 v[118:119], v[30:31], v[118:119]
	v_pk_mul_f32 v[126:127], v[126:127], v[116:117] op_sel_hi:[1,0]
	v_pk_mul_f32 v[124:125], v[124:125], v[116:117] op_sel_hi:[1,0]
	v_pk_mul_f32 v[128:129], v[152:153], v[116:117] op_sel_hi:[1,0]
	v_pk_mul_f32 v[130:131], v[150:151], v[116:117] op_sel_hi:[1,0]
	v_pk_mul_f32 v[120:121], v[120:121], v[116:117] op_sel_hi:[1,0]
	v_pk_mul_f32 v[116:117], v[154:155], v[116:117] op_sel_hi:[1,0]
	v_pk_fma_f32 v[118:119], v[74:75], v[118:119], v[22:23]
	v_pk_mul_f32 v[124:125], v[24:25], v[124:125]
	v_pk_mul_f32 v[126:127], v[26:27], v[126:127]
	v_pk_mul_f32 v[116:117], v[40:41], v[116:117]
	v_pk_mul_f32 v[122:123], v[28:29], v[122:123]
	v_pk_fma_f32 v[126:127], v[78:79], v[126:127], v[18:19]
	v_pk_fma_f32 v[124:125], v[80:81], v[124:125], v[16:17]
	v_pk_mul_f32 v[120:121], v[42:43], v[120:121]
	v_pk_fma_f32 v[150:151], v[88:89], v[116:117], v[32:33]
	v_cvt_pk_bf16_f32 v117, v118, v119
	v_cvt_pk_bf16_f32 v118, v124, v125
	v_cvt_pk_bf16_f32 v119, v126, v127
	v_pk_fma_f32 v[122:123], v[76:77], v[122:123], v[20:21]
	v_pk_mul_f32 v[130:131], v[44:45], v[130:131]
	v_pk_mul_f32 v[128:129], v[46:47], v[128:129]
	v_pk_fma_f32 v[120:121], v[86:87], v[120:121], v[34:35]
	v_cvt_pk_bf16_f32 v116, v122, v123
	global_store_dwordx4 v[94:95], v[116:119], off
	v_pk_fma_f32 v[128:129], v[82:83], v[128:129], v[38:39]
	v_pk_fma_f32 v[130:131], v[84:85], v[130:131], v[36:37]
	v_cvt_pk_bf16_f32 v118, v150, v151
	v_cvt_pk_bf16_f32 v119, v120, v121
	v_cvt_pk_bf16_f32 v117, v128, v129
	s_waitcnt vmcnt(4)
	v_lshlrev_b32_e32 v120, 16, v53
	v_cvt_pk_bf16_f32 v116, v130, v131
	global_store_dwordx4 v[94:95], v[116:119], off offset:1024
	s_waitcnt vmcnt(4)
	v_and_b32_e32 v125, 0xffff0000, v48
	v_and_b32_e32 v124, 0xffff0000, v50
	v_and_b32_e32 v119, 0xffff0000, v54
	v_and_b32_e32 v118, 0xffff0000, v52
	v_lshlrev_b32_e32 v117, 16, v54
	v_lshlrev_b32_e32 v116, 16, v52
	v_and_b32_e32 v54, 0xffff0000, v53
	v_pk_mul_f32 v[52:53], v[118:119], v[118:119]
	v_lshlrev_b32_e32 v121, 16, v55
	v_pk_fma_f32 v[52:53], v[116:117], v[116:117], v[52:53]
	v_lshlrev_b32_e32 v123, 16, v48
	v_lshlrev_b32_e32 v122, 16, v50
	v_lshlrev_b32_e32 v126, 16, v51
	v_and_b32_e32 v48, 0xffff0000, v51
	v_pk_mul_f32 v[50:51], v[124:125], v[124:125]
	v_and_b32_e32 v55, 0xffff0000, v55
	v_pk_fma_f32 v[52:53], v[120:121], v[120:121], v[52:53]
	v_lshlrev_b32_e32 v127, 16, v49
	v_pk_fma_f32 v[50:51], v[122:123], v[122:123], v[50:51]
	v_pk_fma_f32 v[52:53], v[54:55], v[54:55], v[52:53]
	v_and_b32_e32 v49, 0xffff0000, v49
	v_pk_fma_f32 v[50:51], v[126:127], v[126:127], v[50:51]
	v_add_f32_e32 v52, v52, v53
	v_pk_fma_f32 v[50:51], v[48:49], v[48:49], v[50:51]
	v_mov_b32_e32 v53, v54
	v_add_f32_e32 v51, v52, v51
	v_add_f32_e32 v50, v50, v51
	v_mov_b32_e32 v52, v120
	v_mov_b32_e32 v129, v118
	v_add_f32_dpp v50, v50, v50 quad_perm:[1,0,3,2] row_mask:0xf bank_mask:0xf bound_ctrl:1
	v_mov_b32_e32 v54, v121
	v_mov_b32_e32 v118, v117
	v_add_f32_dpp v50, v50, v50 quad_perm:[2,3,0,1] row_mask:0xf bank_mask:0xf bound_ctrl:1
	v_mov_b32_e32 v128, v116
	v_lshl_add_u64 v[94:95], v[94:95], 0, s[30:31]
	v_add_f32_dpp v50, v50, v50 row_half_mirror row_mask:0xf bank_mask:0xf bound_ctrl:1
	s_nop 1
	v_add_f32_dpp v50, v50, v50 row_mirror row_mask:0xf bank_mask:0xf bound_ctrl:1
	s_nop 0
	v_readlane_b32 s6, v50, 16
	v_readlane_b32 s7, v50, 48
	v_readlane_b32 s4, v50, 0
	v_readlane_b32 s5, v50, 32
	v_mov_b32_e32 v50, s6
	v_mov_b32_e32 v51, s7
	v_pk_add_f32 v[50:51], s[4:5], v[50:51]
	s_nop 0
	v_add_f32_e32 v50, v50, v51
	v_fmamk_f32 v50, v50, 0x3a800000, v137
	v_cmp_gt_f32_e32 vcc, s94, v50
	v_mul_f32_e32 v51, 0x4b800000, v50
	s_nop 0
	v_cndmask_b32_e32 v50, v50, v51, vcc
	v_rsq_f32_e32 v50, v50
	s_nop 0
	v_mul_f32_e32 v51, 0x45800000, v50
	v_cndmask_b32_e32 v50, v50, v51, vcc
	v_pk_mul_f32 v[52:53], v[50:51], v[52:53] op_sel_hi:[0,1]
	v_pk_mul_f32 v[52:53], v[6:7], v[52:53]
	v_pk_mul_f32 v[54:55], v[50:51], v[54:55] op_sel_hi:[0,1]
	v_pk_fma_f32 v[52:53], v[58:59], v[52:53], v[114:115]
	v_pk_mul_f32 v[114:115], v[50:51], v[118:119] op_sel_hi:[0,1]
	v_pk_mul_f32 v[114:115], v[0:1], v[114:115]
	v_pk_mul_f32 v[54:55], v[2:3], v[54:55]
	v_pk_fma_f32 v[108:109], v[64:65], v[114:115], v[108:109]
	v_pk_fma_f32 v[54:55], v[62:63], v[54:55], v[110:111]
	v_mov_b32_e32 v110, v127
	v_mov_b32_e32 v111, v49
	v_mov_b32_e32 v114, v123
	v_mov_b32_e32 v115, v125
	v_mov_b32_e32 v127, v48
	v_mov_b32_e32 v123, v124
	v_pk_mul_f32 v[128:129], v[50:51], v[128:129] op_sel_hi:[0,1]
	v_pk_mul_f32 v[110:111], v[50:51], v[110:111] op_sel_hi:[0,1]
	v_pk_mul_f32 v[114:115], v[50:51], v[114:115] op_sel_hi:[0,1]
	v_pk_mul_f32 v[48:49], v[50:51], v[126:127] op_sel_hi:[0,1]
	v_pk_mul_f32 v[50:51], v[50:51], v[122:123] op_sel_hi:[0,1]
	v_pk_mul_f32 v[50:51], v[8:9], v[50:51]
	v_pk_mul_f32 v[128:129], v[4:5], v[128:129]
	v_pk_mul_f32 v[48:49], v[10:11], v[48:49]
	v_pk_fma_f32 v[100:101], v[72:73], v[50:51], v[100:101]
	v_cvt_pk_bf16_f32 v50, v108, v109
	v_cvt_pk_bf16_f32 v51, v54, v55
	v_pk_fma_f32 v[112:113], v[60:61], v[128:129], v[112:113]
	v_pk_mul_f32 v[114:115], v[12:13], v[114:115]
	v_pk_mul_f32 v[110:111], v[14:15], v[110:111]
	v_pk_fma_f32 v[102:103], v[70:71], v[48:49], v[102:103]
	v_cvt_pk_bf16_f32 v48, v112, v113
	v_cvt_pk_bf16_f32 v49, v52, v53
	global_store_dwordx4 v[98:99], v[48:51], off
	v_pk_fma_f32 v[106:107], v[66:67], v[110:111], v[106:107]
	v_pk_fma_f32 v[104:105], v[68:69], v[114:115], v[104:105]
	v_cvt_pk_bf16_f32 v50, v100, v101
	v_cvt_pk_bf16_f32 v51, v102, v103
	v_cvt_pk_bf16_f32 v49, v106, v107
	s_nop 0
	v_cvt_pk_bf16_f32 v48, v104, v105
	global_store_dwordx4 v[98:99], v[48:51], off offset:1024
	v_mov_b32_e32 v98, v101
	v_mov_b32_e32 v99, v105
	v_mov_b32_e32 v50, v113
	v_mov_b32_e32 v51, v109
	v_mov_b32_e32 v48, v112
	v_mov_b32_e32 v49, v108
	v_pk_mul_f32 v[50:51], v[50:51], v[50:51]
	v_pk_mul_f32 v[98:99], v[98:99], v[98:99]
	v_pk_fma_f32 v[48:49], v[48:49], v[48:49], v[50:51]
	v_mov_b32_e32 v50, v52
	v_mov_b32_e32 v51, v54
	v_pk_fma_f32 v[48:49], v[50:51], v[50:51], v[48:49]
	v_mov_b32_e32 v50, v53
	v_mov_b32_e32 v51, v55
	v_pk_fma_f32 v[48:49], v[50:51], v[50:51], v[48:49]
	v_mov_b32_e32 v50, v100
	v_mov_b32_e32 v51, v104
	v_pk_fma_f32 v[50:51], v[50:51], v[50:51], v[98:99]
	v_mov_b32_e32 v98, v102
	v_mov_b32_e32 v99, v106
	v_pk_fma_f32 v[50:51], v[98:99], v[98:99], v[50:51]
	v_mov_b32_e32 v98, v103
	v_mov_b32_e32 v99, v107
	v_pk_fma_f32 v[50:51], v[98:99], v[98:99], v[50:51]
	v_add_f32_e32 v48, v48, v49
	v_add_f32_e32 v48, v51, v48
	v_add_f32_e32 v48, v50, v48
	s_nop 1
	v_add_f32_dpp v48, v48, v48 quad_perm:[1,0,3,2] row_mask:0xf bank_mask:0xf bound_ctrl:1
	s_nop 1
	v_add_f32_dpp v48, v48, v48 quad_perm:[2,3,0,1] row_mask:0xf bank_mask:0xf bound_ctrl:1
	s_nop 1
	v_add_f32_dpp v48, v48, v48 row_half_mirror row_mask:0xf bank_mask:0xf bound_ctrl:1
	s_nop 1
	v_add_f32_dpp v48, v48, v48 row_mirror row_mask:0xf bank_mask:0xf bound_ctrl:1
	s_nop 0
	v_readlane_b32 s6, v48, 16
	v_readlane_b32 s7, v48, 48
	v_readlane_b32 s4, v48, 0
	v_readlane_b32 s5, v48, 32
	v_mov_b32_e32 v48, s6
	v_mov_b32_e32 v49, s7
	v_pk_add_f32 v[48:49], s[4:5], v[48:49]
	s_nop 0
	v_add_f32_e32 v48, v48, v49
	v_fmamk_f32 v48, v48, 0x3a800000, v137
	v_cmp_gt_f32_e32 vcc, s94, v48
	v_mul_f32_e32 v49, 0x4b800000, v48
	s_nop 0
	v_cndmask_b32_e32 v48, v48, v49, vcc
	v_rsq_f32_e32 v48, v48
	s_nop 0
	v_mul_f32_e32 v49, 0x45800000, v48
	v_cndmask_b32_e32 v48, v48, v49, vcc
	v_pk_mul_f32 v[50:51], v[52:53], v[48:49] op_sel_hi:[1,0]
	v_pk_mul_f32 v[52:53], v[112:113], v[48:49] op_sel_hi:[1,0]
	v_pk_mul_f32 v[50:51], v[30:31], v[50:51]
	v_pk_mul_f32 v[54:55], v[54:55], v[48:49] op_sel_hi:[1,0]
	v_pk_mul_f32 v[98:99], v[108:109], v[48:49] op_sel_hi:[1,0]
	v_pk_mul_f32 v[106:107], v[106:107], v[48:49] op_sel_hi:[1,0]
	v_pk_mul_f32 v[104:105], v[104:105], v[48:49] op_sel_hi:[1,0]
	v_pk_mul_f32 v[102:103], v[102:103], v[48:49] op_sel_hi:[1,0]
	v_pk_mul_f32 v[48:49], v[100:101], v[48:49] op_sel_hi:[1,0]
	v_pk_mul_f32 v[52:53], v[28:29], v[52:53]
	v_pk_fma_f32 v[50:51], v[74:75], v[50:51], v[22:23]
	v_pk_mul_f32 v[98:99], v[24:25], v[98:99]
	v_pk_mul_f32 v[54:55], v[26:27], v[54:55]
	v_pk_mul_f32 v[48:49], v[40:41], v[48:49]
	v_pk_fma_f32 v[52:53], v[76:77], v[52:53], v[20:21]
	v_pk_fma_f32 v[54:55], v[78:79], v[54:55], v[18:19]
	v_pk_fma_f32 v[98:99], v[80:81], v[98:99], v[16:17]
	v_pk_mul_f32 v[104:105], v[44:45], v[104:105]
	v_pk_mul_f32 v[106:107], v[46:47], v[106:107]
	v_pk_mul_f32 v[100:101], v[42:43], v[102:103]
	v_pk_fma_f32 v[102:103], v[88:89], v[48:49], v[32:33]
	v_cvt_pk_bf16_f32 v48, v52, v53
	v_cvt_pk_bf16_f32 v49, v50, v51
	v_cvt_pk_bf16_f32 v50, v98, v99
	v_cvt_pk_bf16_f32 v51, v54, v55
	v_pk_fma_f32 v[106:107], v[82:83], v[106:107], v[38:39]
	v_pk_fma_f32 v[104:105], v[84:85], v[104:105], v[36:37]
	v_pk_fma_f32 v[100:101], v[86:87], v[100:101], v[34:35]
	global_store_dwordx4 v[96:97], v[48:51], off
	s_nop 1
	v_cvt_pk_bf16_f32 v48, v104, v105
	v_cvt_pk_bf16_f32 v49, v106, v107
	v_cvt_pk_bf16_f32 v50, v102, v103
	v_cvt_pk_bf16_f32 v51, v100, v101
	global_store_dwordx4 v[96:97], v[48:51], off offset:1024
	s_cbranch_scc1 .LBB0_1086
